# lever 4 mirrored: one static s_setprio 1 for waves 0-3 at kernel entry, all per-segment flips removed
# speedup vs baseline: 1.0009x; 1.0009x over previous
; __global__ void __launch_bounds__(512, 2) fwd_megakernel(Params p) {
;     ...
;     int tid = threadIdx.x; asm volatile("" : "+v"(tid));
;     const int lane = tid & 63, wave = __builtin_amdgcn_readfirstlane(tid >> 6);
_Z14fwd_megakernel6Params:
	v_readfirstlane_b32 s100, v0
	s_nop 3
	s_and_b32 s100, s100, 0x3ff
	s_lshr_b32 s100, s100, 6
	s_cmp_lt_u32 s100, 4
	s_cbranch_scc0 .Lprio_done
	s_setprio 1
